# GLA step 2a: log-sigmoid chains of d-tiles 1 and 3 computed 3-way interleaved (independent dependency chains side by side)
# speedup vs baseline: 1.0091x; 1.0091x over previous
.LBB0_334:
	s_waitcnt vmcnt(6)
	v_perm_b32 v2, v70, v66, s33
	v_perm_b32 v66, v70, v66, s72
	ds_write2_b32 v168, v2, v66 offset1:32
	v_perm_b32 v2, v71, v67, s33
	ds_write_b32 v169, v2 offset:24576
	v_perm_b32 v2, v71, v67, s72
	ds_write_b32 v170, v2 offset:24576
	v_perm_b32 v2, v72, v68, s33
	ds_write_b32 v171, v2 offset:24576
	v_perm_b32 v2, v72, v68, s72
	ds_write_b32 v172, v2 offset:24576
	v_perm_b32 v2, v73, v69, s33
	ds_write_b32 v173, v2 offset:24576
	v_perm_b32 v2, v73, v69, s72
	ds_write_b32 v174, v2 offset:24576
	s_waitcnt vmcnt(5)
	v_perm_b32 v2, v62, v58, s33
	v_perm_b32 v58, v62, v58, s72
	ds_write2_b32 v175, v2, v58 offset1:32
	v_perm_b32 v2, v63, v59, s33
	ds_write_b32 v176, v2 offset:24576
	v_perm_b32 v2, v63, v59, s72
	ds_write_b32 v177, v2 offset:24576
	v_perm_b32 v2, v64, v60, s33
	ds_write_b32 v178, v2 offset:24576
	v_perm_b32 v2, v64, v60, s72
	ds_write_b32 v179, v2 offset:24576
	v_perm_b32 v2, v65, v61, s33
	ds_write_b32 v180, v2 offset:24576
	v_perm_b32 v2, v65, v61, s72
	s_and_b64 vcc, exec, s[4:5]
	v_mov_b64_e32 v[90:91], v[108:109]
	v_mov_b64_e32 v[96:97], v[108:109]
	v_mov_b64_e32 v[94:95], v[116:117]
	v_mov_b64_e32 v[92:93], v[118:119]
	v_mov_b32_e32 v211, v117
	v_mov_b32_e32 v215, v117
	v_mov_b32_e32 v219, v117
	v_mov_b32_e32 v210, v116
	v_mov_b32_e32 v135, v119
	v_mov_b32_e32 v209, v118
	v_mov_b32_e32 v214, v116
	v_mov_b32_e32 v212, v119
	v_mov_b32_e32 v213, v118
	v_mov_b32_e32 v218, v116
	v_mov_b32_e32 v216, v119
	v_mov_b32_e32 v217, v118
	ds_write_b32 v181, v2 offset:24576
	s_cbranch_vccnz .LBB0_303
	s_waitcnt vmcnt(4)
	v_cndmask_b32_e64 v57, 0, v57, s[10:11]
	v_cndmask_b32_e64 v56, 0, v56, s[10:11]
	v_cndmask_b32_e64 v55, 0, v55, s[10:11]
	v_cndmask_b32_e64 v54, 0, v54, s[10:11]
	s_nop 1
	v_mfma_f32_16x16x32_bf16 v[58:61], v[54:57], v[6:9], 0
	v_mfma_f32_16x16x32_bf16 v[62:65], v[54:57], v[10:13], 0
	s_nop 6
	v_add_f32_e32 v2, v111, v58
	v_min_f32_e32 v67, 0, v2
	v_mul_f32_e64 v2, |v2|, s73
	v_exp_f32_e32 v2, v2
	s_nop 0
	v_add_f32_e32 v2, 1.0, v2
	v_log_f32_e32 v2, v2
	s_nop 0
	v_mul_f32_e32 v58, 0x3f317217, v2
	v_fma_f32 v58, v2, s67, -v58
	v_fmac_f32_e32 v58, 0x3377d1cf, v2
	v_fmac_f32_e32 v58, 0x3f317217, v2
	v_mov_b32_e32 v2, v58
	v_mov_b32_e32 v58, 0
	v_sub_f32_e32 v69, v2, v58
	v_add_f32_e32 v2, v111, v59
	v_min_f32_e32 v58, 0, v2
	v_mul_f32_e64 v2, |v2|, s73
	v_exp_f32_e32 v2, v2
	s_nop 0
	v_add_f32_e32 v2, 1.0, v2
	v_log_f32_e32 v2, v2
	s_nop 0
	v_mul_f32_e32 v59, 0x3f317217, v2
	v_fma_f32 v59, v2, s67, -v59
	v_fmac_f32_e32 v59, 0x3377d1cf, v2
	v_fmac_f32_e32 v59, 0x3f317217, v2
	v_mov_b32_e32 v2, v59
	v_mov_b32_e32 v59, 0
	v_sub_f32_e32 v2, v2, v59
	v_sub_f32_e32 v70, v58, v2
	v_add_f32_e32 v2, v111, v60
	v_min_f32_e32 v58, 0, v2
	v_mul_f32_e64 v2, |v2|, s73
	v_exp_f32_e32 v2, v2
	s_nop 0
	v_add_f32_e32 v2, 1.0, v2
	v_log_f32_e32 v2, v2
	s_nop 0
	v_mul_f32_e32 v59, 0x3f317217, v2
	v_fma_f32 v59, v2, s67, -v59
	v_fmac_f32_e32 v59, 0x3377d1cf, v2
	v_fmac_f32_e32 v59, 0x3f317217, v2
	v_mov_b32_e32 v2, v59
	v_mov_b32_e32 v59, 0
	v_sub_f32_e32 v2, v2, v59
	v_sub_f32_e32 v71, v58, v2
	v_add_f32_e32 v2, v111, v61
	v_min_f32_e32 v58, 0, v2
	v_mul_f32_e64 v2, |v2|, s73
	v_exp_f32_e32 v2, v2
	s_nop 0
	v_add_f32_e32 v2, 1.0, v2
	v_log_f32_e32 v2, v2
	s_nop 0
	v_mul_f32_e32 v59, 0x3f317217, v2
	v_fma_f32 v59, v2, s67, -v59
	v_fmac_f32_e32 v59, 0x3377d1cf, v2
	v_fmac_f32_e32 v59, 0x3f317217, v2
	v_mov_b32_e32 v2, v59
	v_mov_b32_e32 v59, 0
	v_sub_f32_e32 v2, v2, v59
	v_sub_f32_e32 v72, v58, v2
	v_add_f32_e32 v2, v139, v62
	v_min_f32_e32 v66, 0, v2
	v_mul_f32_e64 v2, |v2|, s73
	v_exp_f32_e32 v2, v2
	v_and_b32_e32 v62, 64, v1
	v_add_f32_e32 v2, 1.0, v2
	v_log_f32_e32 v2, v2
	s_nop 0
	v_mul_f32_e32 v58, 0x3f317217, v2
	v_fma_f32 v58, v2, s67, -v58
	v_fmac_f32_e32 v58, 0x3377d1cf, v2
	v_fmac_f32_e32 v58, 0x3f317217, v2
	v_mov_b32_e32 v2, v58
	v_mov_b32_e32 v58, 0
	v_sub_f32_e32 v68, v2, v58
	v_add_u32_e32 v2, -16, v1
	v_pk_add_f32 v[58:59], v[66:67], v[68:69] neg_lo:[0,1] neg_hi:[0,1]
	v_cmp_lt_i32_e32 vcc, v2, v62
	v_subrev_u32_e32 v66, 32, v1
	v_pk_mul_f32 v[90:91], v[58:59], s[96:97] op_sel_hi:[1,0]
	v_cndmask_b32_e32 v2, v2, v1, vcc
	v_cmp_lt_i32_e32 vcc, v66, v62
	v_fmamk_f32 v94, v70, 0x3d800000, v91
	v_fmamk_f32 v93, v71, 0x3d800000, v94
	v_cndmask_b32_e32 v66, v66, v1, vcc
	v_lshlrev_b32_e32 v67, 2, v66
	v_subrev_u32_e32 v66, 48, v1
	v_cmp_lt_i32_e32 vcc, v66, v62
	v_lshlrev_b32_e32 v2, 2, v2
	v_or_b32_e32 v62, v62, v166
	v_cndmask_b32_e32 v66, v66, v1, vcc
	v_fmamk_f32 v92, v72, 0x3d800000, v93
	v_lshlrev_b32_e32 v68, 2, v66
	v_lshlrev_b32_e32 v66, 2, v62
	ds_bpermute_b32 v223, v2, v92
	ds_bpermute_b32 v224, v67, v92
	ds_bpermute_b32 v225, v68, v92
	v_mfma_f32_16x16x32_bf16 v[58:61], v[54:57], v[14:17], 0
	v_mfma_f32_16x16x32_bf16 v[54:57], v[54:57], v[18:21], 0
	v_add_f32_e32 v62, v139, v63
	v_add_f32_e32 v63, v139, v64
	v_add_f32_e32 v64, v139, v65
	v_min_f32_e32 v232, 0, v62
	v_min_f32_e32 v233, 0, v63
	v_min_f32_e32 v234, 0, v64
	v_mul_f32_e64 v62, |v62|, s73
	v_mul_f32_e64 v63, |v63|, s73
	v_mul_f32_e64 v64, |v64|, s73
	v_exp_f32_e32 v62, v62
	v_exp_f32_e32 v63, v63
	v_exp_f32_e32 v64, v64
	v_add_f32_e32 v62, 1.0, v62
	v_add_f32_e32 v63, 1.0, v63
	v_add_f32_e32 v64, 1.0, v64
	v_log_f32_e32 v62, v62
	v_log_f32_e32 v63, v63
	v_log_f32_e32 v64, v64
	v_mul_f32_e32 v236, 0x3f317217, v62
	v_mul_f32_e32 v237, 0x3f317217, v63
	v_mul_f32_e32 v238, 0x3f317217, v64
	v_fma_f32 v236, v62, s67, -v236
	v_fma_f32 v237, v63, s67, -v237
	v_fma_f32 v238, v64, s67, -v238
	v_fmac_f32_e32 v236, 0x3377d1cf, v62
	v_fmac_f32_e32 v237, 0x3377d1cf, v63
	v_fmac_f32_e32 v238, 0x3377d1cf, v64
	v_fmac_f32_e32 v236, 0x3f317217, v62
	v_fmac_f32_e32 v237, 0x3f317217, v63
	v_fmac_f32_e32 v238, 0x3f317217, v64
	v_sub_f32_e32 v62, v232, v236
	v_sub_f32_e32 v63, v233, v237
	v_sub_f32_e32 v64, v234, v238
	v_fmamk_f32 v210, v62, 0x3d800000, v90
	v_fmamk_f32 v135, v63, 0x3d800000, v210
	v_fmamk_f32 v209, v64, 0x3d800000, v135
	s_waitcnt lgkmcnt(0)
	v_cndmask_b32_e64 v223, v223, 0, s[6:7]
	v_cndmask_b32_e64 v224, 0, v224, s[12:13]
	v_add_f32_e32 v223, v223, v224
	v_cndmask_b32_e64 v224, 0, v225, s[8:9]
	v_add_f32_e32 v95, v223, v224
	v_add_f32_e32 v223, v95, v92
	ds_bpermute_b32 v220, v66, v223
	ds_bpermute_b32 v226, v2, v209
	ds_bpermute_b32 v227, v67, v209
	ds_bpermute_b32 v228, v68, v209
	v_add_f32_e32 v58, v140, v58
	v_min_f32_e32 v63, 0, v58
	v_mul_f32_e64 v58, |v58|, s73
	v_exp_f32_e32 v58, v58
	v_add_f32_e32 v54, v141, v54
	v_add_f32_e32 v58, 1.0, v58
	s_nop 0
	v_log_f32_e32 v58, v58
	s_nop 0
	v_mul_f32_e32 v62, 0x3f317217, v58
	v_fma_f32 v62, v58, s67, -v62
	v_fmac_f32_e32 v62, 0x3377d1cf, v58
	v_fmac_f32_e32 v62, 0x3f317217, v58
	v_mov_b32_e32 v58, v62
	v_mov_b32_e32 v62, 0
	v_sub_f32_e32 v65, v58, v62
	v_add_f32_e32 v58, v140, v59
	v_min_f32_e32 v59, 0, v58
	v_mul_f32_e64 v58, |v58|, s73
	v_exp_f32_e32 v58, v58
	s_nop 0
	v_add_f32_e32 v58, 1.0, v58
	v_log_f32_e32 v58, v58
	s_nop 0
	v_mul_f32_e32 v62, 0x3f317217, v58
	v_fma_f32 v62, v58, s67, -v62
	v_fmac_f32_e32 v62, 0x3377d1cf, v58
	v_fmac_f32_e32 v62, 0x3f317217, v58
	v_mov_b32_e32 v58, v62
	v_mov_b32_e32 v62, 0
	v_sub_f32_e32 v58, v58, v62
	v_sub_f32_e32 v69, v59, v58
	v_add_f32_e32 v58, v140, v60
	v_min_f32_e32 v59, 0, v58
	v_mul_f32_e64 v58, |v58|, s73
	v_exp_f32_e32 v58, v58
	v_min_f32_e32 v62, 0, v54
	v_mul_f32_e64 v54, |v54|, s73
	v_exp_f32_e32 v54, v54
	v_add_f32_e32 v58, 1.0, v58
	v_add_f32_e32 v54, 1.0, v54
	s_nop 0
	v_log_f32_e32 v58, v58
	s_nop 0
	v_mul_f32_e32 v60, 0x3f317217, v58
	v_fma_f32 v60, v58, s67, -v60
	v_fmac_f32_e32 v60, 0x3377d1cf, v58
	v_fmac_f32_e32 v60, 0x3f317217, v58
	v_mov_b32_e32 v58, v60
	v_mov_b32_e32 v60, 0
	v_sub_f32_e32 v58, v58, v60
	v_sub_f32_e32 v60, v59, v58
	v_add_f32_e32 v58, v140, v61
	v_min_f32_e32 v59, 0, v58
	v_mul_f32_e64 v58, |v58|, s73
	v_exp_f32_e32 v58, v58
	s_nop 0
	v_add_f32_e32 v58, 1.0, v58
	v_log_f32_e32 v58, v58
	s_nop 0
	v_mul_f32_e32 v61, 0x3f317217, v58
	v_fma_f32 v61, v58, s67, -v61
	v_fmac_f32_e32 v61, 0x3377d1cf, v58
	v_fmac_f32_e32 v61, 0x3f317217, v58
	v_mov_b32_e32 v58, v61
	v_mov_b32_e32 v61, 0
	v_sub_f32_e32 v58, v58, v61
	v_sub_f32_e32 v61, v59, v58
	s_nop 0
	v_log_f32_e32 v54, v54
	s_nop 0
	v_mul_f32_e32 v58, 0x3f317217, v54
	v_fma_f32 v58, v54, s67, -v58
	v_fmac_f32_e32 v58, 0x3377d1cf, v54
	v_fmac_f32_e32 v58, 0x3f317217, v54
	v_mov_b32_e32 v54, v58
	v_mov_b32_e32 v58, 0
	v_sub_f32_e32 v64, v54, v58
	v_pk_add_f32 v[58:59], v[62:63], v[64:65] neg_lo:[0,1] neg_hi:[0,1]
	s_nop 0
	v_pk_mul_f32 v[96:97], v[58:59], s[96:97] op_sel_hi:[1,0]
	s_nop 0
	v_fmamk_f32 v214, v69, 0x3d800000, v97
	v_fmamk_f32 v212, v60, 0x3d800000, v214
	v_fmamk_f32 v213, v61, 0x3d800000, v212
	s_and_saveexec_b64 s[0:1], s[6:7]
	s_waitcnt lgkmcnt(3)
	ds_write_b32 v167, v220
	s_or_b64 exec, exec, s[0:1]
	s_waitcnt lgkmcnt(1)
	v_cndmask_b32_e64 v226, v226, 0, s[6:7]
	v_cndmask_b32_e64 v227, 0, v227, s[12:13]
	v_add_f32_e32 v226, v226, v227
	v_cndmask_b32_e64 v227, 0, v228, s[8:9]
	v_add_f32_e32 v211, v226, v227
	v_add_f32_e32 v226, v209, v211
	ds_bpermute_b32 v221, v66, v226
	ds_bpermute_b32 v229, v2, v213
	ds_bpermute_b32 v230, v67, v213
	ds_bpermute_b32 v231, v68, v213
	v_add_f32_e32 v54, v141, v55
	v_add_f32_e32 v55, v141, v56
	v_add_f32_e32 v56, v141, v57
	v_min_f32_e32 v232, 0, v54
	v_min_f32_e32 v233, 0, v55
	v_min_f32_e32 v234, 0, v56
	v_mul_f32_e64 v54, |v54|, s73
	v_mul_f32_e64 v55, |v55|, s73
	v_mul_f32_e64 v56, |v56|, s73
	v_exp_f32_e32 v54, v54
	v_exp_f32_e32 v55, v55
	v_exp_f32_e32 v56, v56
	v_add_f32_e32 v54, 1.0, v54
	v_add_f32_e32 v55, 1.0, v55
	v_add_f32_e32 v56, 1.0, v56
	v_log_f32_e32 v54, v54
	v_log_f32_e32 v55, v55
	v_log_f32_e32 v56, v56
	v_mul_f32_e32 v236, 0x3f317217, v54
	v_mul_f32_e32 v237, 0x3f317217, v55
	v_mul_f32_e32 v238, 0x3f317217, v56
	v_fma_f32 v236, v54, s67, -v236
	v_fma_f32 v237, v55, s67, -v237
	v_fma_f32 v238, v56, s67, -v238
	v_fmac_f32_e32 v236, 0x3377d1cf, v54
	v_fmac_f32_e32 v237, 0x3377d1cf, v55
	v_fmac_f32_e32 v238, 0x3377d1cf, v56
	v_fmac_f32_e32 v236, 0x3f317217, v54
	v_fmac_f32_e32 v237, 0x3f317217, v55
	v_fmac_f32_e32 v238, 0x3f317217, v56
	v_sub_f32_e32 v54, v232, v236
	v_sub_f32_e32 v55, v233, v237
	v_sub_f32_e32 v56, v234, v238
	v_fmamk_f32 v218, v54, 0x3d800000, v96
	v_fmamk_f32 v216, v55, 0x3d800000, v218
	v_fmamk_f32 v217, v56, 0x3d800000, v216
	s_and_saveexec_b64 s[0:1], s[6:7]
	s_waitcnt lgkmcnt(3)
	ds_write_b32 v167, v221 offset:64
	s_or_b64 exec, exec, s[0:1]
	s_waitcnt lgkmcnt(1)
	v_cndmask_b32_e64 v229, v229, 0, s[6:7]
	v_cndmask_b32_e64 v230, 0, v230, s[12:13]
	v_add_f32_e32 v229, v229, v230
	v_cndmask_b32_e64 v230, 0, v231, s[8:9]
	v_add_f32_e32 v215, v229, v230
	v_add_f32_e32 v229, v213, v215
	ds_bpermute_b32 v222, v66, v229
	ds_bpermute_b32 v2, v2, v217
	ds_bpermute_b32 v54, v67, v217
	ds_bpermute_b32 v55, v68, v217
	s_waitcnt lgkmcnt(2)
	v_cndmask_b32_e64 v2, v2, 0, s[6:7]
	s_waitcnt lgkmcnt(1)
	v_cndmask_b32_e64 v54, 0, v54, s[12:13]
	v_add_f32_e32 v2, v2, v54
	s_waitcnt lgkmcnt(0)
	v_cndmask_b32_e64 v54, 0, v55, s[8:9]
	v_add_f32_e32 v219, v2, v54
	v_add_f32_e32 v2, v217, v219
	ds_bpermute_b32 v2, v66, v2
	s_and_saveexec_b64 s[0:1], s[6:7]
	ds_write_b32 v167, v222 offset:128
	s_or_b64 exec, exec, s[0:1]
	s_and_saveexec_b64 s[0:1], s[6:7]
	s_cbranch_execz .LBB0_302
	s_waitcnt lgkmcnt(0)
	ds_write_b32 v167, v2 offset:192
	s_branch .LBB0_302
